# spatial-gating phase: fragment reads of k-steps 2-4 issued one k-step ahead into free registers, counted lgkmcnt before each MFMA (was ds_read -> lgkmcnt(0) -> MFMA, 24 times serial)
# baseline (speedup 1.0000x reference)
; #define LAS __attribute__((address_space(3)))
; __device__ __forceinline__ void spatial_phase(KArgs A, LAS unsigned char* lds, int G) {
;     ...
;             const int t = wave * 16 + fr; const float bsv = b_s[g * 128 + t];
;             const bf16* wrow = WsB + (size_t)(g * 128 + t) * 128 + 8 * fq;
;             bf16x8 wf[4]; v4u uu[4];
; #pragma unroll
;             for (int ks = 0; ks < 4; ++ks) wf[ks] = *(const bf16x8*)(wrow + ks * 32);
; #pragma unroll
;             for (int P = 0; P < 4; ++P) uu[P] = *(const v4u*)(UV + (row0 + t) * 2048 + g * 128 + 32 * P + 8 * fq);
;             __syncthreads();
;             f32x4 acc[4][2];
; #pragma unroll
;             for (int P = 0; P < 4; ++P) { acc[P][0] = (f32x4){0.f, 0.f, 0.f, 0.f}; acc[P][1] = (f32x4){0.f, 0.f, 0.f, 0.f}; }
; #pragma unroll
;             for (int ks = 0; ks < 4; ++ks) {
; #pragma unroll
;                 for (int P = 0; P < 4; ++P)
; #pragma unroll
;                     for (int n = 0; n < 2; ++n) { const int c = 32 * P + 8 * (fr >> 2) + 4 * n + (fr & 3); const int dw = (ks * 16 + 4 * fq) ^ ((((((c >> 3) & 12) | ((0 - (c >> 3)) & 3))) ^ ((c & 3) << 2)) << 2);
;                         const bf16x8 vf = *(const LAS bf16x8*)(tl + c * 64 + dw);
;                         acc[P][n] = __builtin_amdgcn_mfma_f32_16x16x32_bf16(vf, wf[ks], acc[P][n], 0, 0, 0); } }
.LBB0_391:
	s_load_dwordx2 s[42:43], s[0:1], 0x38
	v_ashrrev_i32_e32 v67, 31, v66
	v_lshl_add_u64 v[70:71], v[70:71], 0, s[40:41]
	v_lshl_add_u64 v[68:69], v[68:69], 0, s[40:41]
	s_waitcnt lgkmcnt(0)
	v_lshl_add_u64 v[18:19], v[66:67], 2, s[42:43]
	global_load_dword v105, v[18:19], off
	v_lshlrev_b64 v[18:19], 8, v[66:67]
	v_lshl_add_u64 v[18:19], v[44:45], 0, v[18:19]
	global_load_dwordx4 v[106:109], v[18:19], off
	global_load_dwordx4 v[110:113], v[18:19], off offset:64
	global_load_dwordx4 v[38:41], v[18:19], off offset:128
	global_load_dwordx4 v[34:37], v[18:19], off offset:192
	v_lshl_add_u64 v[18:19], v[64:65], 0, s[20:21]
	v_add3_u32 v67, s27, v0, v81
	global_load_dwordx4 v[30:33], v[18:19], off offset:-128
	global_load_dwordx4 v[26:29], v[18:19], off offset:-64
	global_load_dwordx4 v[22:25], v[18:19], off
	s_nop 0
	global_load_dwordx4 v[18:21], v[18:19], off offset:64
	s_barrier
	ds_read_b128 v[114:117], v67
	ds_read_b128 v[118:121], v67 offset:1024
	v_add3_u32 v67, s27, v82, v81
	ds_read_b128 v[122:125], v67 offset:8192
	ds_read_b128 v[126:129], v67 offset:9216
	v_add3_u32 v67, s27, v83, v81
	ds_read_b128 v[130:133], v67 offset:16384
	ds_read_b128 v[134:137], v67 offset:17408
	v_add3_u32 v67, s27, v84, v81
	ds_read_b128 v[138:141], v67 offset:24576
	ds_read_b128 v[142:145], v67 offset:25600
	v_add3_u32 v67, s27, v85, v81
	v_add_u32_e32 v66, 0x80, v66
	ds_read_b128 v[146:149], v67
	ds_read_b128 v[150:153], v67 offset:1024
	v_add3_u32 v67, s27, v86, v81
	ds_read_b128 v[154:157], v67 offset:8192
	ds_read_b128 v[158:161], v67 offset:9216
	v_add3_u32 v67, s27, v87, v81
	ds_read_b128 v[162:165], v67 offset:16384
	ds_read_b128 v[166:169], v67 offset:17408
	v_add3_u32 v67, s27, v88, v81
	ds_read_b128 v[170:173], v67 offset:24576
	ds_read_b128 v[174:177], v67 offset:25600
	v_add3_u32 v67, s27, v89, v81
	s_waitcnt vmcnt(7) lgkmcnt(15)
	v_mfma_f32_16x16x32_bf16 v[114:117], v[114:117], v[106:109], 0
	s_waitcnt lgkmcnt(14)
	v_mfma_f32_16x16x32_bf16 v[118:121], v[118:121], v[106:109], 0
	s_waitcnt lgkmcnt(13)
	v_mfma_f32_16x16x32_bf16 v[122:125], v[122:125], v[106:109], 0
	s_waitcnt lgkmcnt(12)
	v_mfma_f32_16x16x32_bf16 v[126:129], v[126:129], v[106:109], 0
	s_waitcnt lgkmcnt(11)
	v_mfma_f32_16x16x32_bf16 v[130:133], v[130:133], v[106:109], 0
	s_waitcnt lgkmcnt(10)
	v_mfma_f32_16x16x32_bf16 v[134:137], v[134:137], v[106:109], 0
	s_waitcnt lgkmcnt(9)
	v_mfma_f32_16x16x32_bf16 v[138:141], v[138:141], v[106:109], 0
	s_waitcnt lgkmcnt(8)
	v_mfma_f32_16x16x32_bf16 v[142:145], v[142:145], v[106:109], 0
	ds_read_b128 v[178:181], v67
	ds_read_b128 v[182:185], v67 offset:1024
	v_add3_u32 v67, s27, v90, v81
	ds_read_b128 v[186:189], v67 offset:8192
	ds_read_b128 v[190:193], v67 offset:9216
	v_add3_u32 v67, s27, v91, v81
	ds_read_b128 v[202:205], v67 offset:16384
	ds_read_b128 v[206:209], v67 offset:17408
	v_add3_u32 v67, s27, v92, v81
	ds_read_b128 v[210:213], v67 offset:24576
	ds_read_b128 v[214:217], v67 offset:25600
	v_add3_u32 v67, s27, v93, v81
	s_waitcnt vmcnt(6) lgkmcnt(15)
	v_mfma_f32_16x16x32_bf16 v[114:117], v[146:149], v[110:113], v[114:117]
	s_waitcnt lgkmcnt(14)
	v_mfma_f32_16x16x32_bf16 v[118:121], v[150:153], v[110:113], v[118:121]
	s_waitcnt lgkmcnt(13)
	v_mfma_f32_16x16x32_bf16 v[122:125], v[154:157], v[110:113], v[122:125]
	s_waitcnt lgkmcnt(12)
	v_mfma_f32_16x16x32_bf16 v[126:129], v[158:161], v[110:113], v[126:129]
	s_waitcnt lgkmcnt(11)
	v_mfma_f32_16x16x32_bf16 v[130:133], v[162:165], v[110:113], v[130:133]
	s_waitcnt lgkmcnt(10)
	v_mfma_f32_16x16x32_bf16 v[134:137], v[166:169], v[110:113], v[134:137]
	s_waitcnt lgkmcnt(9)
	v_mfma_f32_16x16x32_bf16 v[138:141], v[170:173], v[110:113], v[138:141]
	s_waitcnt lgkmcnt(8)
	v_mfma_f32_16x16x32_bf16 v[142:145], v[174:177], v[110:113], v[142:145]
	ds_read_b128 v[146:149], v67
	ds_read_b128 v[150:153], v67 offset:1024
	v_add3_u32 v67, s27, v94, v81
	ds_read_b128 v[154:157], v67 offset:8192
	ds_read_b128 v[158:161], v67 offset:9216
	v_add3_u32 v67, s27, v95, v81
	ds_read_b128 v[162:165], v67 offset:16384
	ds_read_b128 v[166:169], v67 offset:17408
	v_add3_u32 v67, s27, v96, v81
	ds_read_b128 v[170:173], v67 offset:24576
	ds_read_b128 v[174:177], v67 offset:25600
	s_waitcnt vmcnt(5) lgkmcnt(15)
	v_mfma_f32_16x16x32_bf16 v[114:117], v[178:181], v[38:41], v[114:117]
	s_waitcnt lgkmcnt(14)
	v_mfma_f32_16x16x32_bf16 v[118:121], v[182:185], v[38:41], v[118:121]
	s_waitcnt lgkmcnt(13)
	v_mfma_f32_16x16x32_bf16 v[122:125], v[186:189], v[38:41], v[122:125]
	s_waitcnt lgkmcnt(12)
	v_mfma_f32_16x16x32_bf16 v[126:129], v[190:193], v[38:41], v[126:129]
	s_waitcnt lgkmcnt(11)
	v_mfma_f32_16x16x32_bf16 v[130:133], v[202:205], v[38:41], v[130:133]
	s_waitcnt lgkmcnt(10)
	v_mfma_f32_16x16x32_bf16 v[134:137], v[206:209], v[38:41], v[134:137]
	s_waitcnt lgkmcnt(9)
	v_mfma_f32_16x16x32_bf16 v[138:141], v[210:213], v[38:41], v[138:141]
	s_waitcnt lgkmcnt(8)
; #define LAS __attribute__((address_space(3)))
; __device__ __forceinline__ unsigned pk2(float lo, float hi) { return pg8::cvt_pk_bf16(lo, hi); }
; __device__ __forceinline__ float bflo(unsigned w) { return __uint_as_float(w << 16); }
; __device__ __forceinline__ float bfhi(unsigned w) { return __uint_as_float(w & 0xffff0000u); }
; __device__ __forceinline__ void spatial_phase(KArgs A, LAS unsigned char* lds, int G) {
;     ...
;             for (int ks = 0; ks < 4; ++ks) {
; #pragma unroll
;                 for (int P = 0; P < 4; ++P)
; #pragma unroll
;                     for (int n = 0; n < 2; ++n) { const int c = 32 * P + 8 * (fr >> 2) + 4 * n + (fr & 3); const int dw = (ks * 16 + 4 * fq) ^ ((((((c >> 3) & 12) | ((0 - (c >> 3)) & 3))) ^ ((c & 3) << 2)) << 2);
;                         const bf16x8 vf = *(const LAS bf16x8*)(tl + c * 64 + dw);
;                         acc[P][n] = __builtin_amdgcn_mfma_f32_16x16x32_bf16(vf, wf[ks], acc[P][n], 0, 0, 0); } }
; #pragma unroll
;             for (int P = 0; P < 4; ++P) { const int c0 = g * 128 + 32 * P + 8 * fq; const v4u u4 = uu[P];
;                 v4u o; o.x = pk2(bflo(u4.x) * (acc[P][0][0] + bsv), bfhi(u4.x) * (acc[P][0][1] + bsv)); o.y = pk2(bflo(u4.y) * (acc[P][0][2] + bsv), bfhi(u4.y) * (acc[P][0][3] + bsv));
;                 o.z = pk2(bflo(u4.z) * (acc[P][1][0] + bsv), bfhi(u4.z) * (acc[P][1][1] + bsv)); o.w = pk2(bflo(u4.w) * (acc[P][1][2] + bsv), bfhi(u4.w) * (acc[P][1][3] + bsv));
;                 *(v4u*)(GT + (row0 + t) * D + c0) = o; }
	v_mfma_f32_16x16x32_bf16 v[142:145], v[214:217], v[38:41], v[142:145]
	s_waitcnt vmcnt(4) lgkmcnt(7)
	v_mfma_f32_16x16x32_bf16 v[114:117], v[146:149], v[34:37], v[114:117]
	s_waitcnt lgkmcnt(6)
	v_mfma_f32_16x16x32_bf16 v[118:121], v[150:153], v[34:37], v[118:121]
	s_waitcnt lgkmcnt(5)
	v_mfma_f32_16x16x32_bf16 v[122:125], v[154:157], v[34:37], v[122:125]
	s_waitcnt lgkmcnt(4)
	v_mfma_f32_16x16x32_bf16 v[126:129], v[158:161], v[34:37], v[126:129]
	s_waitcnt lgkmcnt(3)
	v_mfma_f32_16x16x32_bf16 v[130:133], v[162:165], v[34:37], v[130:133]
	s_waitcnt lgkmcnt(2)
	v_mfma_f32_16x16x32_bf16 v[134:137], v[166:169], v[34:37], v[134:137]
	s_waitcnt lgkmcnt(1)
	v_mfma_f32_16x16x32_bf16 v[138:141], v[170:173], v[34:37], v[138:141]
	s_waitcnt lgkmcnt(0)
	v_mfma_f32_16x16x32_bf16 v[142:145], v[174:177], v[34:37], v[142:145]
	s_waitcnt vmcnt(3)
	v_lshlrev_b32_e32 v67, 16, v30
	v_and_b32_e32 v30, 0xffff0000, v30
	s_nop 2
	v_add_f32_e32 v106, v105, v114
	v_mul_f32_e32 v67, v106, v67
	v_add_f32_e32 v106, v105, v115
	v_mul_f32_e32 v30, v106, v30
	v_cvt_pk_bf16_f32 v30, v67, v30
	v_lshlrev_b32_e32 v67, 16, v31
	v_add_f32_e32 v106, v105, v116
	v_mul_f32_e32 v67, v106, v67
	v_and_b32_e32 v31, 0xffff0000, v31
	v_add_f32_e32 v106, v105, v117
	v_mul_f32_e32 v31, v106, v31
	v_cvt_pk_bf16_f32 v31, v67, v31
	v_lshlrev_b32_e32 v67, 16, v32
	v_add_f32_e32 v106, v105, v118
	v_mul_f32_e32 v67, v106, v67
	v_and_b32_e32 v32, 0xffff0000, v32
	v_add_f32_e32 v106, v105, v119
	v_mul_f32_e32 v32, v106, v32
	v_cvt_pk_bf16_f32 v32, v67, v32
	v_lshlrev_b32_e32 v67, 16, v33
	v_add_f32_e32 v106, v105, v120
	v_mul_f32_e32 v67, v106, v67
	v_and_b32_e32 v33, 0xffff0000, v33
	v_add_f32_e32 v106, v105, v121
	v_mul_f32_e32 v33, v106, v33
	v_lshl_add_u64 v[106:107], v[60:61], 0, s[20:21]
	v_cvt_pk_bf16_f32 v33, v67, v33
	global_store_dwordx4 v[106:107], v[30:33], off offset:-128
	s_add_u32 s20, s20, 0x100
	s_addc_u32 s21, s21, 0
	s_waitcnt vmcnt(3)
	v_lshlrev_b32_e32 v30, 16, v26
	v_add_f32_e32 v31, v105, v122
	v_mul_f32_e32 v30, v31, v30
	v_and_b32_e32 v26, 0xffff0000, v26
	v_add_f32_e32 v31, v105, v123
	v_mul_f32_e32 v26, v31, v26
	v_cvt_pk_bf16_f32 v26, v30, v26
	v_lshlrev_b32_e32 v30, 16, v27
	v_add_f32_e32 v31, v105, v124
	v_mul_f32_e32 v30, v31, v30
	v_and_b32_e32 v27, 0xffff0000, v27
	v_add_f32_e32 v31, v105, v125
	v_mul_f32_e32 v27, v31, v27
	v_cvt_pk_bf16_f32 v27, v30, v27
	v_lshlrev_b32_e32 v30, 16, v28
	v_add_f32_e32 v31, v105, v126
	v_mul_f32_e32 v30, v31, v30
	v_and_b32_e32 v28, 0xffff0000, v28
	v_add_f32_e32 v31, v105, v127
	v_mul_f32_e32 v28, v31, v28
	v_cvt_pk_bf16_f32 v28, v30, v28
	v_lshlrev_b32_e32 v30, 16, v29
	v_add_f32_e32 v31, v105, v128
	v_mul_f32_e32 v30, v31, v30
	v_and_b32_e32 v29, 0xffff0000, v29
	v_add_f32_e32 v31, v105, v129
	v_mul_f32_e32 v29, v31, v29
	v_cvt_pk_bf16_f32 v29, v30, v29
	global_store_dwordx4 v[106:107], v[26:29], off offset:-64
	s_addk_i32 s7, 0x2000
	s_cmpk_eq_i32 s20, 0x800
	s_waitcnt vmcnt(3)
	v_lshlrev_b32_e32 v26, 16, v22
	v_add_f32_e32 v27, v105, v130
	v_mul_f32_e32 v26, v27, v26
	v_and_b32_e32 v22, 0xffff0000, v22
	v_add_f32_e32 v27, v105, v131
	v_mul_f32_e32 v22, v27, v22
	v_cvt_pk_bf16_f32 v22, v26, v22
	v_lshlrev_b32_e32 v26, 16, v23
	v_add_f32_e32 v27, v105, v132
	v_mul_f32_e32 v26, v27, v26
	v_and_b32_e32 v23, 0xffff0000, v23
	v_add_f32_e32 v27, v105, v133
	v_mul_f32_e32 v23, v27, v23
	v_cvt_pk_bf16_f32 v23, v26, v23
	v_lshlrev_b32_e32 v26, 16, v24
	v_add_f32_e32 v27, v105, v134
	v_mul_f32_e32 v26, v27, v26
	v_and_b32_e32 v24, 0xffff0000, v24
	v_add_f32_e32 v27, v105, v135
	v_mul_f32_e32 v24, v27, v24
	v_cvt_pk_bf16_f32 v24, v26, v24
	v_lshlrev_b32_e32 v26, 16, v25
	v_add_f32_e32 v27, v105, v136
	v_mul_f32_e32 v26, v27, v26
	v_and_b32_e32 v25, 0xffff0000, v25
	v_add_f32_e32 v27, v105, v137
	v_mul_f32_e32 v25, v27, v25
	v_cvt_pk_bf16_f32 v25, v26, v25
	global_store_dwordx4 v[106:107], v[22:25], off
	s_waitcnt vmcnt(3)
	s_nop 0
	v_lshlrev_b32_e32 v22, 16, v18
	v_add_f32_e32 v23, v105, v138
	v_mul_f32_e32 v22, v23, v22
	v_and_b32_e32 v18, 0xffff0000, v18
	v_add_f32_e32 v23, v105, v139
	v_mul_f32_e32 v18, v23, v18
	v_cvt_pk_bf16_f32 v18, v22, v18
	v_lshlrev_b32_e32 v22, 16, v19
	v_add_f32_e32 v23, v105, v140
	v_mul_f32_e32 v22, v23, v22
	v_and_b32_e32 v19, 0xffff0000, v19
	v_add_f32_e32 v23, v105, v141
	v_mul_f32_e32 v19, v23, v19
	v_cvt_pk_bf16_f32 v19, v22, v19
	v_lshlrev_b32_e32 v22, 16, v20
	v_add_f32_e32 v23, v105, v142
	v_mul_f32_e32 v22, v23, v22
	v_and_b32_e32 v20, 0xffff0000, v20
	v_add_f32_e32 v23, v105, v143
	v_mul_f32_e32 v20, v23, v20
	v_cvt_pk_bf16_f32 v20, v22, v20
	v_lshlrev_b32_e32 v22, 16, v21
	v_add_f32_e32 v23, v105, v144
	v_mul_f32_e32 v22, v23, v22
	v_and_b32_e32 v21, 0xffff0000, v21
	v_add_f32_e32 v23, v105, v145
	v_mul_f32_e32 v21, v23, v21
	v_cvt_pk_bf16_f32 v21, v22, v21
	global_store_dwordx4 v[106:107], v[18:21], off offset:64
	s_cbranch_scc1 .LBB0_389
